# in-projection epilogue: 7 per-tile row-address recomputations (64-bit multiply chains) replaced by one 64-bit add of a scalar byte delta; on top of chain+gla_prep+scalar-base GEMM DMAs
# baseline (speedup 1.0000x reference)
; __device__ __forceinline__ unsigned cvt_pk(float lo, float hi) { unsigned r; asm volatile("v_cvt_pk_bf16_f32 %0, %1, %2" : "=v"(r) : "v"(lo), "v"(hi)); return r; }
;     __device__ __forceinline__ void operator()(const f32x4 (&acc)[2][2][4][2], const Unit& u, int wr, int wc, int fr, int fq) const {
;     ...
;         const int row0 = u.pm * BM + wr * 64 + fr, col0 = colt + wc * 32 + 8 * fq;
; #pragma unroll
;         for (int ai = 0; ai < 2; ++ai)
; #pragma unroll
;             for (int m = 0; m < 4; ++m) { const int row = row0 + ai * HALF + m * 16; const float rs = sc; bf16_t* rowp = base + (size_t)row * ldc + col0;
; #pragma unroll
;                 for (int bj = 0; bj < 2; ++bj) { const f32x4 v0 = acc[ai][bj][m][0] * rs, v1 = acc[ai][bj][m][1] * rs;
;                     u32x4 w; w.x = cvt_pk(v0[0], v0[1]); w.y = cvt_pk(v0[2], v0[3]); w.z = cvt_pk(v1[0], v1[1]); w.w = cvt_pk(v1[2], v1[3]);
;                     if (pn == 4 || pn == 5) *(u32x4*)((pn == 4 ? KB : VB) + ((size_t)bj * 40960 + row) * 128 + wc * 32 + 8 * fq) = w;
;                     else if (pn >= 18) __builtin_nontemporal_store(w, (u32x4*)(rowp + bj * HALF));
;                     else *(u32x4*)(rowp + bj * HALF) = w; } }
.LBB0_221:
	s_nop 1
	v_or_b32_e32 v116, 16, v154
	v_ashrrev_i32_e32 v117, 31, v116
	v_mov_b32_e32 v118, v150
	v_mov_b32_e32 v119, v150
	s_mul_i32 s88, s30, 0x20
	s_mul_hi_u32 s89, s30, 0x20
	s_mul_i32 s90, s31, 0x20
	s_add_i32 s89, s89, s90
	v_lshl_add_u64 v[114:115], v[156:157], 0, s[88:89]
	v_pk_mul_f32 v[112:113], v[112:113], v[118:119]
	v_pk_mul_f32 v[118:119], v[108:109], v[118:119]
	v_pk_mul_f32 v[108:109], v[106:107], v[150:151]
	s_and_b64 vcc, exec, s[2:3]
	s_mov_b64 s[34:35], -1
	v_pk_mul_f32 v[110:111], v[110:111], v[150:151]
	s_nop 0
	v_cvt_pk_bf16_f32 v106, v110, v111
	v_cvt_pk_bf16_f32 v107, v112, v113
	v_cvt_pk_bf16_f32 v108, v108, v109
	v_cvt_pk_bf16_f32 v109, v118, v119
	s_cbranch_vccnz .LBB0_223
	s_mov_b64 s[34:35], 0
	global_store_dwordx4 v[114:115], v[106:109], off

; __device__ __forceinline__ unsigned cvt_pk(float lo, float hi) { unsigned r; asm volatile("v_cvt_pk_bf16_f32 %0, %1, %2" : "=v"(r) : "v"(lo), "v"(hi)); return r; }
;     __device__ __forceinline__ void operator()(const f32x4 (&acc)[2][2][4][2], const Unit& u, int wr, int wc, int fr, int fq) const {
;     ...
;         const int row0 = u.pm * BM + wr * 64 + fr, col0 = colt + wc * 32 + 8 * fq;
; #pragma unroll
;         for (int ai = 0; ai < 2; ++ai)
; #pragma unroll
;             for (int m = 0; m < 4; ++m) { const int row = row0 + ai * HALF + m * 16; const float rs = sc; bf16_t* rowp = base + (size_t)row * ldc + col0;
; #pragma unroll
;                 for (int bj = 0; bj < 2; ++bj) { const f32x4 v0 = acc[ai][bj][m][0] * rs, v1 = acc[ai][bj][m][1] * rs;
;                     u32x4 w; w.x = cvt_pk(v0[0], v0[1]); w.y = cvt_pk(v0[2], v0[3]); w.z = cvt_pk(v1[0], v1[1]); w.w = cvt_pk(v1[2], v1[3]);
;                     if (pn == 4 || pn == 5) *(u32x4*)((pn == 4 ? KB : VB) + ((size_t)bj * 40960 + row) * 128 + wc * 32 + 8 * fq) = w;
;                     else if (pn >= 18) __builtin_nontemporal_store(w, (u32x4*)(rowp + bj * HALF));
;                     else *(u32x4*)(rowp + bj * HALF) = w; } }
.LBB0_229:
	s_nop 1
	v_or_b32_e32 v100, 32, v154
	v_ashrrev_i32_e32 v101, 31, v100
	v_mov_b32_e32 v102, v150
	v_mov_b32_e32 v103, v150
	s_mul_i32 s88, s30, 0x40
	s_mul_hi_u32 s89, s30, 0x40
	s_mul_i32 s90, s31, 0x40
	s_add_i32 s89, s89, s90
	v_lshl_add_u64 v[98:99], v[156:157], 0, s[88:89]
	v_pk_mul_f32 v[96:97], v[96:97], v[102:103]
	v_pk_mul_f32 v[102:103], v[92:93], v[102:103]
	v_pk_mul_f32 v[92:93], v[90:91], v[150:151]
	s_and_b64 vcc, exec, s[2:3]
	s_mov_b64 s[34:35], -1
	v_pk_mul_f32 v[94:95], v[94:95], v[150:151]
	s_nop 0
	v_cvt_pk_bf16_f32 v90, v94, v95
	v_cvt_pk_bf16_f32 v91, v96, v97
	v_cvt_pk_bf16_f32 v92, v92, v93
	v_cvt_pk_bf16_f32 v93, v102, v103
	s_cbranch_vccnz .LBB0_231
	s_mov_b64 s[34:35], 0
	global_store_dwordx4 v[98:99], v[90:93], off

; __device__ __forceinline__ unsigned cvt_pk(float lo, float hi) { unsigned r; asm volatile("v_cvt_pk_bf16_f32 %0, %1, %2" : "=v"(r) : "v"(lo), "v"(hi)); return r; }
;     __device__ __forceinline__ void operator()(const f32x4 (&acc)[2][2][4][2], const Unit& u, int wr, int wc, int fr, int fq) const {
;     ...
;         const int row0 = u.pm * BM + wr * 64 + fr, col0 = colt + wc * 32 + 8 * fq;
; #pragma unroll
;         for (int ai = 0; ai < 2; ++ai)
; #pragma unroll
;             for (int m = 0; m < 4; ++m) { const int row = row0 + ai * HALF + m * 16; const float rs = sc; bf16_t* rowp = base + (size_t)row * ldc + col0;
; #pragma unroll
;                 for (int bj = 0; bj < 2; ++bj) { const f32x4 v0 = acc[ai][bj][m][0] * rs, v1 = acc[ai][bj][m][1] * rs;
;                     u32x4 w; w.x = cvt_pk(v0[0], v0[1]); w.y = cvt_pk(v0[2], v0[3]); w.z = cvt_pk(v1[0], v1[1]); w.w = cvt_pk(v1[2], v1[3]);
;                     if (pn == 4 || pn == 5) *(u32x4*)((pn == 4 ? KB : VB) + ((size_t)bj * 40960 + row) * 128 + wc * 32 + 8 * fq) = w;
;                     else if (pn >= 18) __builtin_nontemporal_store(w, (u32x4*)(rowp + bj * HALF));
;                     else *(u32x4*)(rowp + bj * HALF) = w; } }
.LBB0_237:
	s_nop 1
	v_or_b32_e32 v84, 48, v154
	v_ashrrev_i32_e32 v85, 31, v84
	v_mov_b32_e32 v86, v150
	v_mov_b32_e32 v87, v150
	s_mul_i32 s88, s30, 0x60
	s_mul_hi_u32 s89, s30, 0x60
	s_mul_i32 s90, s31, 0x60
	s_add_i32 s89, s89, s90
	v_lshl_add_u64 v[82:83], v[156:157], 0, s[88:89]
	v_pk_mul_f32 v[80:81], v[80:81], v[86:87]
	v_pk_mul_f32 v[86:87], v[76:77], v[86:87]
	v_pk_mul_f32 v[76:77], v[74:75], v[150:151]
	s_and_b64 vcc, exec, s[2:3]
	s_mov_b64 s[34:35], -1
	v_pk_mul_f32 v[78:79], v[78:79], v[150:151]
	s_nop 0
	v_cvt_pk_bf16_f32 v74, v78, v79
	v_cvt_pk_bf16_f32 v75, v80, v81
	v_cvt_pk_bf16_f32 v76, v76, v77
	v_cvt_pk_bf16_f32 v77, v86, v87
	s_cbranch_vccnz .LBB0_239
	s_mov_b64 s[34:35], 0
	global_store_dwordx4 v[82:83], v[74:77], off

; __device__ __forceinline__ unsigned cvt_pk(float lo, float hi) { unsigned r; asm volatile("v_cvt_pk_bf16_f32 %0, %1, %2" : "=v"(r) : "v"(lo), "v"(hi)); return r; }
;     __device__ __forceinline__ void operator()(const f32x4 (&acc)[2][2][4][2], const Unit& u, int wr, int wc, int fr, int fq) const {
;     ...
;         const int row0 = u.pm * BM + wr * 64 + fr, col0 = colt + wc * 32 + 8 * fq;
; #pragma unroll
;         for (int ai = 0; ai < 2; ++ai)
; #pragma unroll
;             for (int m = 0; m < 4; ++m) { const int row = row0 + ai * HALF + m * 16; const float rs = sc; bf16_t* rowp = base + (size_t)row * ldc + col0;
; #pragma unroll
;                 for (int bj = 0; bj < 2; ++bj) { const f32x4 v0 = acc[ai][bj][m][0] * rs, v1 = acc[ai][bj][m][1] * rs;
;                     u32x4 w; w.x = cvt_pk(v0[0], v0[1]); w.y = cvt_pk(v0[2], v0[3]); w.z = cvt_pk(v1[0], v1[1]); w.w = cvt_pk(v1[2], v1[3]);
;                     if (pn == 4 || pn == 5) *(u32x4*)((pn == 4 ? KB : VB) + ((size_t)bj * 40960 + row) * 128 + wc * 32 + 8 * fq) = w;
;                     else if (pn >= 18) __builtin_nontemporal_store(w, (u32x4*)(rowp + bj * HALF));
;                     else *(u32x4*)(rowp + bj * HALF) = w; } }
.LBB0_245:
	s_nop 1
	v_add_u32_e32 v68, 0x80, v154
	v_ashrrev_i32_e32 v69, 31, v68
	v_mov_b32_e32 v70, v150
	v_mov_b32_e32 v71, v150
	s_mul_i32 s88, s30, 0x100
	s_mul_hi_u32 s89, s30, 0x100
	s_mul_i32 s90, s31, 0x100
	s_add_i32 s89, s89, s90
	v_lshl_add_u64 v[66:67], v[156:157], 0, s[88:89]
	v_pk_mul_f32 v[64:65], v[64:65], v[70:71]
	v_pk_mul_f32 v[70:71], v[60:61], v[70:71]
	v_pk_mul_f32 v[60:61], v[58:59], v[150:151]
	s_and_b64 vcc, exec, s[2:3]
	s_mov_b64 s[34:35], -1
	v_pk_mul_f32 v[62:63], v[62:63], v[150:151]
	s_nop 0
	v_cvt_pk_bf16_f32 v58, v62, v63
	v_cvt_pk_bf16_f32 v59, v64, v65
	v_cvt_pk_bf16_f32 v60, v60, v61
	v_cvt_pk_bf16_f32 v61, v70, v71
	s_cbranch_vccnz .LBB0_247
	s_mov_b64 s[34:35], 0
	global_store_dwordx4 v[66:67], v[58:61], off

; __device__ __forceinline__ unsigned cvt_pk(float lo, float hi) { unsigned r; asm volatile("v_cvt_pk_bf16_f32 %0, %1, %2" : "=v"(r) : "v"(lo), "v"(hi)); return r; }
;     __device__ __forceinline__ void operator()(const f32x4 (&acc)[2][2][4][2], const Unit& u, int wr, int wc, int fr, int fq) const {
;     ...
;         const int row0 = u.pm * BM + wr * 64 + fr, col0 = colt + wc * 32 + 8 * fq;
; #pragma unroll
;         for (int ai = 0; ai < 2; ++ai)
; #pragma unroll
;             for (int m = 0; m < 4; ++m) { const int row = row0 + ai * HALF + m * 16; const float rs = sc; bf16_t* rowp = base + (size_t)row * ldc + col0;
; #pragma unroll
;                 for (int bj = 0; bj < 2; ++bj) { const f32x4 v0 = acc[ai][bj][m][0] * rs, v1 = acc[ai][bj][m][1] * rs;
;                     u32x4 w; w.x = cvt_pk(v0[0], v0[1]); w.y = cvt_pk(v0[2], v0[3]); w.z = cvt_pk(v1[0], v1[1]); w.w = cvt_pk(v1[2], v1[3]);
;                     if (pn == 4 || pn == 5) *(u32x4*)((pn == 4 ? KB : VB) + ((size_t)bj * 40960 + row) * 128 + wc * 32 + 8 * fq) = w;
;                     else if (pn >= 18) __builtin_nontemporal_store(w, (u32x4*)(rowp + bj * HALF));
;                     else *(u32x4*)(rowp + bj * HALF) = w; } }
.LBB0_253:
	s_nop 1
	v_add_u32_e32 v52, 0x90, v154
	v_ashrrev_i32_e32 v53, 31, v52
	v_mov_b32_e32 v54, v150
	v_mov_b32_e32 v55, v150
	s_mul_i32 s88, s30, 0x120
	s_mul_hi_u32 s89, s30, 0x120
	s_mul_i32 s90, s31, 0x120
	s_add_i32 s89, s89, s90
	v_lshl_add_u64 v[50:51], v[156:157], 0, s[88:89]
	v_pk_mul_f32 v[48:49], v[48:49], v[54:55]
	v_pk_mul_f32 v[54:55], v[44:45], v[54:55]
	v_pk_mul_f32 v[44:45], v[42:43], v[150:151]
	s_and_b64 vcc, exec, s[2:3]
	s_mov_b64 s[34:35], -1
	v_pk_mul_f32 v[46:47], v[46:47], v[150:151]
	s_nop 0
	v_cvt_pk_bf16_f32 v42, v46, v47
	v_cvt_pk_bf16_f32 v43, v48, v49
	v_cvt_pk_bf16_f32 v44, v44, v45
	v_cvt_pk_bf16_f32 v45, v54, v55
	s_cbranch_vccnz .LBB0_255
	s_mov_b64 s[34:35], 0
	global_store_dwordx4 v[50:51], v[42:45], off

; __device__ __forceinline__ unsigned cvt_pk(float lo, float hi) { unsigned r; asm volatile("v_cvt_pk_bf16_f32 %0, %1, %2" : "=v"(r) : "v"(lo), "v"(hi)); return r; }
;     __device__ __forceinline__ void operator()(const f32x4 (&acc)[2][2][4][2], const Unit& u, int wr, int wc, int fr, int fq) const {
;     ...
;         const int row0 = u.pm * BM + wr * 64 + fr, col0 = colt + wc * 32 + 8 * fq;
; #pragma unroll
;         for (int ai = 0; ai < 2; ++ai)
; #pragma unroll
;             for (int m = 0; m < 4; ++m) { const int row = row0 + ai * HALF + m * 16; const float rs = sc; bf16_t* rowp = base + (size_t)row * ldc + col0;
; #pragma unroll
;                 for (int bj = 0; bj < 2; ++bj) { const f32x4 v0 = acc[ai][bj][m][0] * rs, v1 = acc[ai][bj][m][1] * rs;
;                     u32x4 w; w.x = cvt_pk(v0[0], v0[1]); w.y = cvt_pk(v0[2], v0[3]); w.z = cvt_pk(v1[0], v1[1]); w.w = cvt_pk(v1[2], v1[3]);
;                     if (pn == 4 || pn == 5) *(u32x4*)((pn == 4 ? KB : VB) + ((size_t)bj * 40960 + row) * 128 + wc * 32 + 8 * fq) = w;
;                     else if (pn >= 18) __builtin_nontemporal_store(w, (u32x4*)(rowp + bj * HALF));
;                     else *(u32x4*)(rowp + bj * HALF) = w; } }
.LBB0_261:
	s_nop 1
	v_add_u32_e32 v36, 0xa0, v154
	v_ashrrev_i32_e32 v37, 31, v36
	v_mov_b32_e32 v38, v150
	v_mov_b32_e32 v39, v150
	s_mul_i32 s88, s30, 0x140
	s_mul_hi_u32 s89, s30, 0x140
	s_mul_i32 s90, s31, 0x140
	s_add_i32 s89, s89, s90
	v_lshl_add_u64 v[34:35], v[156:157], 0, s[88:89]
	v_pk_mul_f32 v[32:33], v[32:33], v[38:39]
	v_pk_mul_f32 v[38:39], v[28:29], v[38:39]
	v_pk_mul_f32 v[28:29], v[26:27], v[150:151]
	s_and_b64 vcc, exec, s[2:3]
	s_mov_b64 s[34:35], -1
	v_pk_mul_f32 v[30:31], v[30:31], v[150:151]
	s_nop 0
	v_cvt_pk_bf16_f32 v26, v30, v31
	v_cvt_pk_bf16_f32 v27, v32, v33
	v_cvt_pk_bf16_f32 v28, v28, v29
	v_cvt_pk_bf16_f32 v29, v38, v39
	s_cbranch_vccnz .LBB0_263
	s_mov_b64 s[34:35], 0
	global_store_dwordx4 v[34:35], v[26:29], off

; __device__ __forceinline__ unsigned cvt_pk(float lo, float hi) { unsigned r; asm volatile("v_cvt_pk_bf16_f32 %0, %1, %2" : "=v"(r) : "v"(lo), "v"(hi)); return r; }
;     __device__ __forceinline__ void operator()(const f32x4 (&acc)[2][2][4][2], const Unit& u, int wr, int wc, int fr, int fq) const {
;     ...
;         const int row0 = u.pm * BM + wr * 64 + fr, col0 = colt + wc * 32 + 8 * fq;
; #pragma unroll
;         for (int ai = 0; ai < 2; ++ai)
; #pragma unroll
;             for (int m = 0; m < 4; ++m) { const int row = row0 + ai * HALF + m * 16; const float rs = sc; bf16_t* rowp = base + (size_t)row * ldc + col0;
; #pragma unroll
;                 for (int bj = 0; bj < 2; ++bj) { const f32x4 v0 = acc[ai][bj][m][0] * rs, v1 = acc[ai][bj][m][1] * rs;
;                     u32x4 w; w.x = cvt_pk(v0[0], v0[1]); w.y = cvt_pk(v0[2], v0[3]); w.z = cvt_pk(v1[0], v1[1]); w.w = cvt_pk(v1[2], v1[3]);
;                     if (pn == 4 || pn == 5) *(u32x4*)((pn == 4 ? KB : VB) + ((size_t)bj * 40960 + row) * 128 + wc * 32 + 8 * fq) = w;
;                     else if (pn >= 18) __builtin_nontemporal_store(w, (u32x4*)(rowp + bj * HALF));
;                     else *(u32x4*)(rowp + bj * HALF) = w; } }
.LBB0_269:
	s_nop 1
	v_add_u32_e32 v20, 0xb0, v154
	v_ashrrev_i32_e32 v21, 31, v20
	v_mov_b32_e32 v22, v150
	v_mov_b32_e32 v23, v150
	s_mul_i32 s88, s30, 0x160
	s_mul_hi_u32 s89, s30, 0x160
	s_mul_i32 s90, s31, 0x160
	s_add_i32 s89, s89, s90
	v_lshl_add_u64 v[18:19], v[156:157], 0, s[88:89]
	v_pk_mul_f32 v[16:17], v[16:17], v[22:23]
	v_pk_mul_f32 v[22:23], v[12:13], v[22:23]
	v_pk_mul_f32 v[12:13], v[10:11], v[150:151]
	s_and_b64 vcc, exec, s[2:3]
	s_mov_b64 s[30:31], -1
	v_pk_mul_f32 v[14:15], v[14:15], v[150:151]
	s_nop 0
	v_cvt_pk_bf16_f32 v10, v14, v15
	v_cvt_pk_bf16_f32 v11, v16, v17
	v_cvt_pk_bf16_f32 v12, v12, v13
	v_cvt_pk_bf16_f32 v13, v22, v23
	s_cbranch_vccnz .LBB0_271
	s_mov_b64 s[30:31], 0
	global_store_dwordx4 v[18:19], v[10:13], off

; __device__ __forceinline__ unsigned cvt_pk(float lo, float hi) { unsigned r; asm volatile("v_cvt_pk_bf16_f32 %0, %1, %2" : "=v"(r) : "v"(lo), "v"(hi)); return r; }
;     __device__ __forceinline__ void operator()(const f32x4 (&acc)[2][2][4][2], const Unit& u, int wr, int wc, int fr, int fq) const {
;     ...
;         const int row0 = u.pm * BM + wr * 64 + fr, col0 = colt + wc * 32 + 8 * fq;
; #pragma unroll
;         for (int ai = 0; ai < 2; ++ai)
; #pragma unroll
;             for (int m = 0; m < 4; ++m) { const int row = row0 + ai * HALF + m * 16; const float rs = sc; bf16_t* rowp = base + (size_t)row * ldc + col0;
; #pragma unroll
;                 for (int bj = 0; bj < 2; ++bj) { const f32x4 v0 = acc[ai][bj][m][0] * rs, v1 = acc[ai][bj][m][1] * rs;
;                     u32x4 w; w.x = cvt_pk(v0[0], v0[1]); w.y = cvt_pk(v0[2], v0[3]); w.z = cvt_pk(v1[0], v1[1]); w.w = cvt_pk(v1[2], v1[3]);
;                     if (pn == 4 || pn == 5) *(u32x4*)((pn == 4 ? KB : VB) + ((size_t)bj * 40960 + row) * 128 + wc * 32 + 8 * fq) = w;
;                     else if (pn >= 18) __builtin_nontemporal_store(w, (u32x4*)(rowp + bj * HALF));
;                     else *(u32x4*)(rowp + bj * HALF) = w; } }
.LBB0_783:
	s_nop 1
	v_or_b32_e32 v116, 16, v156
	v_ashrrev_i32_e32 v117, 31, v116
	v_mov_b32_e32 v118, v152
	v_mov_b32_e32 v119, v152
	s_mul_i32 s88, s30, 0x20
	s_mul_hi_u32 s89, s30, 0x20
	s_mul_i32 s90, s31, 0x20
	s_add_i32 s89, s89, s90
	v_lshl_add_u64 v[114:115], v[158:159], 0, s[88:89]
	v_pk_mul_f32 v[112:113], v[112:113], v[118:119]
	v_pk_mul_f32 v[118:119], v[108:109], v[118:119]
	v_pk_mul_f32 v[108:109], v[106:107], v[152:153]
	s_and_b64 vcc, exec, s[2:3]
	s_mov_b64 s[34:35], -1
	v_pk_mul_f32 v[110:111], v[110:111], v[152:153]
	s_nop 0
	v_cvt_pk_bf16_f32 v106, v110, v111
	v_cvt_pk_bf16_f32 v107, v112, v113
	v_cvt_pk_bf16_f32 v108, v108, v109
	v_cvt_pk_bf16_f32 v109, v118, v119
	s_cbranch_vccnz .LBB0_785
	s_mov_b64 s[34:35], 0
	global_store_dwordx4 v[114:115], v[106:109], off

; __device__ __forceinline__ unsigned cvt_pk(float lo, float hi) { unsigned r; asm volatile("v_cvt_pk_bf16_f32 %0, %1, %2" : "=v"(r) : "v"(lo), "v"(hi)); return r; }
;     __device__ __forceinline__ void operator()(const f32x4 (&acc)[2][2][4][2], const Unit& u, int wr, int wc, int fr, int fq) const {
;     ...
;         const int row0 = u.pm * BM + wr * 64 + fr, col0 = colt + wc * 32 + 8 * fq;
; #pragma unroll
;         for (int ai = 0; ai < 2; ++ai)
; #pragma unroll
;             for (int m = 0; m < 4; ++m) { const int row = row0 + ai * HALF + m * 16; const float rs = sc; bf16_t* rowp = base + (size_t)row * ldc + col0;
; #pragma unroll
;                 for (int bj = 0; bj < 2; ++bj) { const f32x4 v0 = acc[ai][bj][m][0] * rs, v1 = acc[ai][bj][m][1] * rs;
;                     u32x4 w; w.x = cvt_pk(v0[0], v0[1]); w.y = cvt_pk(v0[2], v0[3]); w.z = cvt_pk(v1[0], v1[1]); w.w = cvt_pk(v1[2], v1[3]);
;                     if (pn == 4 || pn == 5) *(u32x4*)((pn == 4 ? KB : VB) + ((size_t)bj * 40960 + row) * 128 + wc * 32 + 8 * fq) = w;
;                     else if (pn >= 18) __builtin_nontemporal_store(w, (u32x4*)(rowp + bj * HALF));
;                     else *(u32x4*)(rowp + bj * HALF) = w; } }
.LBB0_791:
	s_nop 1
	v_or_b32_e32 v100, 32, v156
	v_ashrrev_i32_e32 v101, 31, v100
	v_mov_b32_e32 v102, v152
	v_mov_b32_e32 v103, v152
	s_mul_i32 s88, s30, 0x40
	s_mul_hi_u32 s89, s30, 0x40
	s_mul_i32 s90, s31, 0x40
	s_add_i32 s89, s89, s90
	v_lshl_add_u64 v[98:99], v[158:159], 0, s[88:89]
	v_pk_mul_f32 v[96:97], v[96:97], v[102:103]
	v_pk_mul_f32 v[102:103], v[92:93], v[102:103]
	v_pk_mul_f32 v[92:93], v[90:91], v[152:153]
	s_and_b64 vcc, exec, s[2:3]
	s_mov_b64 s[34:35], -1
	v_pk_mul_f32 v[94:95], v[94:95], v[152:153]
	s_nop 0
	v_cvt_pk_bf16_f32 v90, v94, v95
	v_cvt_pk_bf16_f32 v91, v96, v97
	v_cvt_pk_bf16_f32 v92, v92, v93
	v_cvt_pk_bf16_f32 v93, v102, v103
	s_cbranch_vccnz .LBB0_793
	s_mov_b64 s[34:35], 0
	global_store_dwordx4 v[98:99], v[90:93], off

; __device__ __forceinline__ unsigned cvt_pk(float lo, float hi) { unsigned r; asm volatile("v_cvt_pk_bf16_f32 %0, %1, %2" : "=v"(r) : "v"(lo), "v"(hi)); return r; }
;     __device__ __forceinline__ void operator()(const f32x4 (&acc)[2][2][4][2], const Unit& u, int wr, int wc, int fr, int fq) const {
;     ...
;         const int row0 = u.pm * BM + wr * 64 + fr, col0 = colt + wc * 32 + 8 * fq;
; #pragma unroll
;         for (int ai = 0; ai < 2; ++ai)
; #pragma unroll
;             for (int m = 0; m < 4; ++m) { const int row = row0 + ai * HALF + m * 16; const float rs = sc; bf16_t* rowp = base + (size_t)row * ldc + col0;
; #pragma unroll
;                 for (int bj = 0; bj < 2; ++bj) { const f32x4 v0 = acc[ai][bj][m][0] * rs, v1 = acc[ai][bj][m][1] * rs;
;                     u32x4 w; w.x = cvt_pk(v0[0], v0[1]); w.y = cvt_pk(v0[2], v0[3]); w.z = cvt_pk(v1[0], v1[1]); w.w = cvt_pk(v1[2], v1[3]);
;                     if (pn == 4 || pn == 5) *(u32x4*)((pn == 4 ? KB : VB) + ((size_t)bj * 40960 + row) * 128 + wc * 32 + 8 * fq) = w;
;                     else if (pn >= 18) __builtin_nontemporal_store(w, (u32x4*)(rowp + bj * HALF));
;                     else *(u32x4*)(rowp + bj * HALF) = w; } }
.LBB0_799:
	s_nop 1
	v_or_b32_e32 v84, 48, v156
	v_ashrrev_i32_e32 v85, 31, v84
	v_mov_b32_e32 v86, v152
	v_mov_b32_e32 v87, v152
	s_mul_i32 s88, s30, 0x60
	s_mul_hi_u32 s89, s30, 0x60
	s_mul_i32 s90, s31, 0x60
	s_add_i32 s89, s89, s90
	v_lshl_add_u64 v[82:83], v[158:159], 0, s[88:89]
	v_pk_mul_f32 v[80:81], v[80:81], v[86:87]
	v_pk_mul_f32 v[86:87], v[76:77], v[86:87]
	v_pk_mul_f32 v[76:77], v[74:75], v[152:153]
	s_and_b64 vcc, exec, s[2:3]
	s_mov_b64 s[34:35], -1
	v_pk_mul_f32 v[78:79], v[78:79], v[152:153]
	s_nop 0
	v_cvt_pk_bf16_f32 v74, v78, v79
	v_cvt_pk_bf16_f32 v75, v80, v81
	v_cvt_pk_bf16_f32 v76, v76, v77
	v_cvt_pk_bf16_f32 v77, v86, v87
	s_cbranch_vccnz .LBB0_801
	s_mov_b64 s[34:35], 0
	global_store_dwordx4 v[82:83], v[74:77], off

; __device__ __forceinline__ unsigned cvt_pk(float lo, float hi) { unsigned r; asm volatile("v_cvt_pk_bf16_f32 %0, %1, %2" : "=v"(r) : "v"(lo), "v"(hi)); return r; }
;     __device__ __forceinline__ void operator()(const f32x4 (&acc)[2][2][4][2], const Unit& u, int wr, int wc, int fr, int fq) const {
;     ...
;         const int row0 = u.pm * BM + wr * 64 + fr, col0 = colt + wc * 32 + 8 * fq;
; #pragma unroll
;         for (int ai = 0; ai < 2; ++ai)
; #pragma unroll
;             for (int m = 0; m < 4; ++m) { const int row = row0 + ai * HALF + m * 16; const float rs = sc; bf16_t* rowp = base + (size_t)row * ldc + col0;
; #pragma unroll
;                 for (int bj = 0; bj < 2; ++bj) { const f32x4 v0 = acc[ai][bj][m][0] * rs, v1 = acc[ai][bj][m][1] * rs;
;                     u32x4 w; w.x = cvt_pk(v0[0], v0[1]); w.y = cvt_pk(v0[2], v0[3]); w.z = cvt_pk(v1[0], v1[1]); w.w = cvt_pk(v1[2], v1[3]);
;                     if (pn == 4 || pn == 5) *(u32x4*)((pn == 4 ? KB : VB) + ((size_t)bj * 40960 + row) * 128 + wc * 32 + 8 * fq) = w;
;                     else if (pn >= 18) __builtin_nontemporal_store(w, (u32x4*)(rowp + bj * HALF));
;                     else *(u32x4*)(rowp + bj * HALF) = w; } }
.LBB0_807:
	s_nop 1
	v_add_u32_e32 v68, 0x80, v156
	v_ashrrev_i32_e32 v69, 31, v68
	v_mov_b32_e32 v70, v152
	v_mov_b32_e32 v71, v152
	s_mul_i32 s88, s30, 0x100
	s_mul_hi_u32 s89, s30, 0x100
	s_mul_i32 s90, s31, 0x100
	s_add_i32 s89, s89, s90
	v_lshl_add_u64 v[66:67], v[158:159], 0, s[88:89]
	v_pk_mul_f32 v[64:65], v[64:65], v[70:71]
	v_pk_mul_f32 v[70:71], v[60:61], v[70:71]
	v_pk_mul_f32 v[60:61], v[58:59], v[152:153]
	s_and_b64 vcc, exec, s[2:3]
	s_mov_b64 s[34:35], -1
	v_pk_mul_f32 v[62:63], v[62:63], v[152:153]
	s_nop 0
	v_cvt_pk_bf16_f32 v58, v62, v63
	v_cvt_pk_bf16_f32 v59, v64, v65
	v_cvt_pk_bf16_f32 v60, v60, v61
	v_cvt_pk_bf16_f32 v61, v70, v71
	s_cbranch_vccnz .LBB0_809
	s_mov_b64 s[34:35], 0
	global_store_dwordx4 v[66:67], v[58:61], off

; __device__ __forceinline__ unsigned cvt_pk(float lo, float hi) { unsigned r; asm volatile("v_cvt_pk_bf16_f32 %0, %1, %2" : "=v"(r) : "v"(lo), "v"(hi)); return r; }
;     __device__ __forceinline__ void operator()(const f32x4 (&acc)[2][2][4][2], const Unit& u, int wr, int wc, int fr, int fq) const {
;     ...
;         const int row0 = u.pm * BM + wr * 64 + fr, col0 = colt + wc * 32 + 8 * fq;
; #pragma unroll
;         for (int ai = 0; ai < 2; ++ai)
; #pragma unroll
;             for (int m = 0; m < 4; ++m) { const int row = row0 + ai * HALF + m * 16; const float rs = sc; bf16_t* rowp = base + (size_t)row * ldc + col0;
; #pragma unroll
;                 for (int bj = 0; bj < 2; ++bj) { const f32x4 v0 = acc[ai][bj][m][0] * rs, v1 = acc[ai][bj][m][1] * rs;
;                     u32x4 w; w.x = cvt_pk(v0[0], v0[1]); w.y = cvt_pk(v0[2], v0[3]); w.z = cvt_pk(v1[0], v1[1]); w.w = cvt_pk(v1[2], v1[3]);
;                     if (pn == 4 || pn == 5) *(u32x4*)((pn == 4 ? KB : VB) + ((size_t)bj * 40960 + row) * 128 + wc * 32 + 8 * fq) = w;
;                     else if (pn >= 18) __builtin_nontemporal_store(w, (u32x4*)(rowp + bj * HALF));
;                     else *(u32x4*)(rowp + bj * HALF) = w; } }
.LBB0_815:
	s_nop 1
	v_add_u32_e32 v52, 0x90, v156
	v_ashrrev_i32_e32 v53, 31, v52
	v_mov_b32_e32 v54, v152
	v_mov_b32_e32 v55, v152
	s_mul_i32 s88, s30, 0x120
	s_mul_hi_u32 s89, s30, 0x120
	s_mul_i32 s90, s31, 0x120
	s_add_i32 s89, s89, s90
	v_lshl_add_u64 v[50:51], v[158:159], 0, s[88:89]
	v_pk_mul_f32 v[48:49], v[48:49], v[54:55]
	v_pk_mul_f32 v[54:55], v[44:45], v[54:55]
	v_pk_mul_f32 v[44:45], v[42:43], v[152:153]
	s_and_b64 vcc, exec, s[2:3]
	s_mov_b64 s[34:35], -1
	v_pk_mul_f32 v[46:47], v[46:47], v[152:153]
	s_nop 0
	v_cvt_pk_bf16_f32 v42, v46, v47
	v_cvt_pk_bf16_f32 v43, v48, v49
	v_cvt_pk_bf16_f32 v44, v44, v45
	v_cvt_pk_bf16_f32 v45, v54, v55
	s_cbranch_vccnz .LBB0_817
	s_mov_b64 s[34:35], 0
	global_store_dwordx4 v[50:51], v[42:45], off

; __device__ __forceinline__ unsigned cvt_pk(float lo, float hi) { unsigned r; asm volatile("v_cvt_pk_bf16_f32 %0, %1, %2" : "=v"(r) : "v"(lo), "v"(hi)); return r; }
;     __device__ __forceinline__ void operator()(const f32x4 (&acc)[2][2][4][2], const Unit& u, int wr, int wc, int fr, int fq) const {
;     ...
;         const int row0 = u.pm * BM + wr * 64 + fr, col0 = colt + wc * 32 + 8 * fq;
; #pragma unroll
;         for (int ai = 0; ai < 2; ++ai)
; #pragma unroll
;             for (int m = 0; m < 4; ++m) { const int row = row0 + ai * HALF + m * 16; const float rs = sc; bf16_t* rowp = base + (size_t)row * ldc + col0;
; #pragma unroll
;                 for (int bj = 0; bj < 2; ++bj) { const f32x4 v0 = acc[ai][bj][m][0] * rs, v1 = acc[ai][bj][m][1] * rs;
;                     u32x4 w; w.x = cvt_pk(v0[0], v0[1]); w.y = cvt_pk(v0[2], v0[3]); w.z = cvt_pk(v1[0], v1[1]); w.w = cvt_pk(v1[2], v1[3]);
;                     if (pn == 4 || pn == 5) *(u32x4*)((pn == 4 ? KB : VB) + ((size_t)bj * 40960 + row) * 128 + wc * 32 + 8 * fq) = w;
;                     else if (pn >= 18) __builtin_nontemporal_store(w, (u32x4*)(rowp + bj * HALF));
;                     else *(u32x4*)(rowp + bj * HALF) = w; } }
.LBB0_823:
	s_nop 1
	v_add_u32_e32 v36, 0xa0, v156
	v_ashrrev_i32_e32 v37, 31, v36
	v_mov_b32_e32 v38, v152
	v_mov_b32_e32 v39, v152
	s_mul_i32 s88, s30, 0x140
	s_mul_hi_u32 s89, s30, 0x140
	s_mul_i32 s90, s31, 0x140
	s_add_i32 s89, s89, s90
	v_lshl_add_u64 v[34:35], v[158:159], 0, s[88:89]
	v_pk_mul_f32 v[32:33], v[32:33], v[38:39]
	v_pk_mul_f32 v[38:39], v[28:29], v[38:39]
	v_pk_mul_f32 v[28:29], v[26:27], v[152:153]
	s_and_b64 vcc, exec, s[2:3]
	s_mov_b64 s[34:35], -1
	v_pk_mul_f32 v[30:31], v[30:31], v[152:153]
	s_nop 0
	v_cvt_pk_bf16_f32 v26, v30, v31
	v_cvt_pk_bf16_f32 v27, v32, v33
	v_cvt_pk_bf16_f32 v28, v28, v29
	v_cvt_pk_bf16_f32 v29, v38, v39
	s_cbranch_vccnz .LBB0_825
	s_mov_b64 s[34:35], 0
	global_store_dwordx4 v[34:35], v[26:29], off

; __device__ __forceinline__ unsigned cvt_pk(float lo, float hi) { unsigned r; asm volatile("v_cvt_pk_bf16_f32 %0, %1, %2" : "=v"(r) : "v"(lo), "v"(hi)); return r; }
;     __device__ __forceinline__ void operator()(const f32x4 (&acc)[2][2][4][2], const Unit& u, int wr, int wc, int fr, int fq) const {
;     ...
;         const int row0 = u.pm * BM + wr * 64 + fr, col0 = colt + wc * 32 + 8 * fq;
; #pragma unroll
;         for (int ai = 0; ai < 2; ++ai)
; #pragma unroll
;             for (int m = 0; m < 4; ++m) { const int row = row0 + ai * HALF + m * 16; const float rs = sc; bf16_t* rowp = base + (size_t)row * ldc + col0;
; #pragma unroll
;                 for (int bj = 0; bj < 2; ++bj) { const f32x4 v0 = acc[ai][bj][m][0] * rs, v1 = acc[ai][bj][m][1] * rs;
;                     u32x4 w; w.x = cvt_pk(v0[0], v0[1]); w.y = cvt_pk(v0[2], v0[3]); w.z = cvt_pk(v1[0], v1[1]); w.w = cvt_pk(v1[2], v1[3]);
;                     if (pn == 4 || pn == 5) *(u32x4*)((pn == 4 ? KB : VB) + ((size_t)bj * 40960 + row) * 128 + wc * 32 + 8 * fq) = w;
;                     else if (pn >= 18) __builtin_nontemporal_store(w, (u32x4*)(rowp + bj * HALF));
;                     else *(u32x4*)(rowp + bj * HALF) = w; } }
.LBB0_831:
	s_nop 1
	v_add_u32_e32 v20, 0xb0, v156
	v_ashrrev_i32_e32 v21, 31, v20
	v_mov_b32_e32 v22, v152
	v_mov_b32_e32 v23, v152
	s_mul_i32 s88, s30, 0x160
	s_mul_hi_u32 s89, s30, 0x160
	s_mul_i32 s90, s31, 0x160
	s_add_i32 s89, s89, s90
	v_lshl_add_u64 v[18:19], v[158:159], 0, s[88:89]
	v_pk_mul_f32 v[16:17], v[16:17], v[22:23]
	v_pk_mul_f32 v[22:23], v[12:13], v[22:23]
	v_pk_mul_f32 v[12:13], v[10:11], v[152:153]
	s_and_b64 vcc, exec, s[2:3]
	s_mov_b64 s[30:31], -1
	v_pk_mul_f32 v[14:15], v[14:15], v[152:153]
	s_nop 0
	v_cvt_pk_bf16_f32 v10, v14, v15
	v_cvt_pk_bf16_f32 v11, v16, v17
	v_cvt_pk_bf16_f32 v12, v12, v13
	v_cvt_pk_bf16_f32 v13, v22, v23
	s_cbranch_vccnz .LBB0_833
	s_mov_b64 s[30:31], 0
	global_store_dwordx4 v[18:19], v[10:13], off
